# gate phase: all kmean loads of an item batched up front (plus OWN combine batching)
# baseline (speedup 1.0000x reference)
.LBB0_271:
	s_barrier
	s_and_saveexec_b64 s[10:11], s[6:7]
	ds_write_b32 v41, v159
	s_or_b64 exec, exec, s[10:11]
	s_and_b32 s0, s47, 0xffffff80
	s_and_b32 s72, s39, 7
	v_add_u32_e32 v36, s0, v42
	s_lshl_b32 s48, s72, 14
	v_ashrrev_i32_e32 v37, 31, v36
	v_lshl_add_u64 v[0:1], v[36:37], 0, s[48:49]
	v_lshlrev_b64 v[0:1], 8, v[0:1]
	v_lshl_add_u64 v[0:1], v[32:33], 0, v[0:1]
	s_waitcnt lgkmcnt(0)
	s_barrier
	global_load_dwordx4 v[20:23], v[0:1], off
	global_load_dwordx4 v[16:19], v[0:1], off offset:64
	global_load_dwordx4 v[12:15], v[0:1], off offset:128
	s_nop 0
	global_load_dwordx4 v[0:3], v[0:1], off offset:192
	s_ashr_i32 s48, s39, 4
	s_add_i32 s0, s48, 15
	s_ashr_i32 s0, s0, 4
	v_mov_b32_e32 v4, 0
	s_cmp_lt_i32 s0, 1
	v_lshl_or_b32 v158, s72, 15, v62
	v_mov_b32_e32 v8, 0
	v_mov_b32_e32 v9, 0
	v_mov_b32_e32 v10, 0
	v_mov_b32_e32 v11, 0
	s_cbranch_scc1 .LBB0_275
	v_lshl_add_u64 v[202:203], v[34:35], 0, v[158:159]
	global_load_dwordx4 v[76:79], v[202:203], off
	global_load_dwordx4 v[80:83], v[202:203], off offset:16
	global_load_dwordx4 v[84:87], v[202:203], off offset:128
	global_load_dwordx4 v[88:91], v[202:203], off offset:144
	global_load_dwordx4 v[92:95], v[202:203], off offset:256
	global_load_dwordx4 v[96:99], v[202:203], off offset:272
	global_load_dwordx4 v[100:103], v[202:203], off offset:384
	global_load_dwordx4 v[104:107], v[202:203], off offset:400
	s_mov_b64 s[10:11], 0x2000
	v_lshl_add_u64 v[204:205], v[202:203], 0, s[10:11]
	global_load_dwordx4 v[108:111], v[204:205], off
	global_load_dwordx4 v[112:115], v[204:205], off offset:16
	global_load_dwordx4 v[116:119], v[204:205], off offset:128
	global_load_dwordx4 v[120:123], v[204:205], off offset:144
	global_load_dwordx4 v[124:127], v[204:205], off offset:256
	global_load_dwordx4 v[128:131], v[204:205], off offset:272
	global_load_dwordx4 v[132:135], v[204:205], off offset:384
	global_load_dwordx4 v[136:139], v[204:205], off offset:400
	s_mov_b64 s[10:11], 0x4000
	v_lshl_add_u64 v[204:205], v[202:203], 0, s[10:11]
	global_load_dwordx4 v[140:143], v[204:205], off
	global_load_dwordx4 v[144:147], v[204:205], off offset:16
	global_load_dwordx4 v[148:151], v[204:205], off offset:128
	global_load_dwordx4 v[152:155], v[204:205], off offset:144
	global_load_dwordx4 v[166:169], v[204:205], off offset:256
	global_load_dwordx4 v[170:173], v[204:205], off offset:272
	global_load_dwordx4 v[174:177], v[204:205], off offset:384
	global_load_dwordx4 v[178:181], v[204:205], off offset:400
	s_mov_b64 s[10:11], 0x6000
	v_lshl_add_u64 v[204:205], v[202:203], 0, s[10:11]
	global_load_dwordx4 v[182:185], v[204:205], off
	global_load_dwordx4 v[186:189], v[204:205], off offset:16
	global_load_dwordx4 v[214:217], v[204:205], off offset:128
	global_load_dwordx4 v[218:221], v[204:205], off offset:144
	global_load_dwordx4 v[222:225], v[204:205], off offset:256
	global_load_dwordx4 v[226:229], v[204:205], off offset:272
	global_load_dwordx4 v[230:233], v[204:205], off offset:384
	global_load_dwordx4 v[234:237], v[204:205], off offset:400
	s_waitcnt vmcnt(30)
	v_cvt_pk_bf16_f32 v64, v76, v77
	v_cvt_pk_bf16_f32 v65, v78, v79
	v_cvt_pk_bf16_f32 v66, v80, v81
	v_cvt_pk_bf16_f32 v67, v82, v83
	v_lshlrev_b32_e32 v190, 16, v64
	v_and_b32_e32 v191, 0xffff0000, v64
	v_sub_f32_e32 v190, v76, v190
	v_sub_f32_e32 v191, v77, v191
	v_cvt_pk_bf16_f32 v70, v190, v191
	v_lshlrev_b32_e32 v190, 16, v65
	v_and_b32_e32 v191, 0xffff0000, v65
	v_sub_f32_e32 v190, v78, v190
	v_sub_f32_e32 v191, v79, v191
	v_cvt_pk_bf16_f32 v71, v190, v191
	v_lshlrev_b32_e32 v190, 16, v66
	v_and_b32_e32 v191, 0xffff0000, v66
	v_sub_f32_e32 v190, v80, v190
	v_sub_f32_e32 v191, v81, v191
	v_cvt_pk_bf16_f32 v72, v190, v191
	v_lshlrev_b32_e32 v190, 16, v67
	v_and_b32_e32 v191, 0xffff0000, v67
	v_sub_f32_e32 v190, v82, v190
	v_sub_f32_e32 v191, v83, v191
	v_cvt_pk_bf16_f32 v73, v190, v191
	s_nop 1
	v_mfma_f32_16x16x32_bf16 v[8:11], v[64:67], v[20:23], 0
	v_mfma_f32_16x16x32_bf16 v[8:11], v[70:73], v[20:23], v[8:11]
	s_waitcnt vmcnt(28)
	v_cvt_pk_bf16_f32 v64, v84, v85
	v_cvt_pk_bf16_f32 v65, v86, v87
	v_cvt_pk_bf16_f32 v66, v88, v89
	v_cvt_pk_bf16_f32 v67, v90, v91
	v_lshlrev_b32_e32 v190, 16, v64
	v_and_b32_e32 v191, 0xffff0000, v64
	v_sub_f32_e32 v190, v84, v190
	v_sub_f32_e32 v191, v85, v191
	v_cvt_pk_bf16_f32 v70, v190, v191
	v_lshlrev_b32_e32 v190, 16, v65
	v_and_b32_e32 v191, 0xffff0000, v65
	v_sub_f32_e32 v190, v86, v190
	v_sub_f32_e32 v191, v87, v191
	v_cvt_pk_bf16_f32 v71, v190, v191
	v_lshlrev_b32_e32 v190, 16, v66
	v_and_b32_e32 v191, 0xffff0000, v66
	v_sub_f32_e32 v190, v88, v190
	v_sub_f32_e32 v191, v89, v191
	v_cvt_pk_bf16_f32 v72, v190, v191
	v_lshlrev_b32_e32 v190, 16, v67
	v_and_b32_e32 v191, 0xffff0000, v67
	v_sub_f32_e32 v190, v90, v190
	v_sub_f32_e32 v191, v91, v191
	v_cvt_pk_bf16_f32 v73, v190, v191
	s_nop 1
	v_mfma_f32_16x16x32_bf16 v[8:11], v[64:67], v[16:19], v[8:11]
	v_mfma_f32_16x16x32_bf16 v[8:11], v[70:73], v[16:19], v[8:11]
	s_waitcnt vmcnt(26)
	v_cvt_pk_bf16_f32 v64, v92, v93
	v_cvt_pk_bf16_f32 v65, v94, v95
	v_cvt_pk_bf16_f32 v66, v96, v97
	v_cvt_pk_bf16_f32 v67, v98, v99
	v_lshlrev_b32_e32 v190, 16, v64
	v_and_b32_e32 v191, 0xffff0000, v64
	v_sub_f32_e32 v190, v92, v190
	v_sub_f32_e32 v191, v93, v191
	v_cvt_pk_bf16_f32 v70, v190, v191
	v_lshlrev_b32_e32 v190, 16, v65
	v_and_b32_e32 v191, 0xffff0000, v65
	v_sub_f32_e32 v190, v94, v190
	v_sub_f32_e32 v191, v95, v191
	v_cvt_pk_bf16_f32 v71, v190, v191
	v_lshlrev_b32_e32 v190, 16, v66
	v_and_b32_e32 v191, 0xffff0000, v66
	v_sub_f32_e32 v190, v96, v190
	v_sub_f32_e32 v191, v97, v191
	v_cvt_pk_bf16_f32 v72, v190, v191
	v_lshlrev_b32_e32 v190, 16, v67
	v_and_b32_e32 v191, 0xffff0000, v67
	v_sub_f32_e32 v190, v98, v190
	v_sub_f32_e32 v191, v99, v191
	v_cvt_pk_bf16_f32 v73, v190, v191
	s_nop 1
	v_mfma_f32_16x16x32_bf16 v[8:11], v[64:67], v[12:15], v[8:11]
	v_mfma_f32_16x16x32_bf16 v[8:11], v[70:73], v[12:15], v[8:11]
	s_waitcnt vmcnt(24)
	v_cvt_pk_bf16_f32 v64, v100, v101
	v_cvt_pk_bf16_f32 v65, v102, v103
	v_cvt_pk_bf16_f32 v66, v104, v105
	v_cvt_pk_bf16_f32 v67, v106, v107
	v_lshlrev_b32_e32 v190, 16, v64
	v_and_b32_e32 v191, 0xffff0000, v64
	v_sub_f32_e32 v190, v100, v190
	v_sub_f32_e32 v191, v101, v191
	v_cvt_pk_bf16_f32 v70, v190, v191
	v_lshlrev_b32_e32 v190, 16, v65
	v_and_b32_e32 v191, 0xffff0000, v65
	v_sub_f32_e32 v190, v102, v190
	v_sub_f32_e32 v191, v103, v191
	v_cvt_pk_bf16_f32 v71, v190, v191
	v_lshlrev_b32_e32 v190, 16, v66
	v_and_b32_e32 v191, 0xffff0000, v66
	v_sub_f32_e32 v190, v104, v190
	v_sub_f32_e32 v191, v105, v191
	v_cvt_pk_bf16_f32 v72, v190, v191
	v_lshlrev_b32_e32 v190, 16, v67
	v_and_b32_e32 v191, 0xffff0000, v67
	v_sub_f32_e32 v190, v106, v190
	v_sub_f32_e32 v191, v107, v191
	v_cvt_pk_bf16_f32 v73, v190, v191
	s_nop 1
	v_mfma_f32_16x16x32_bf16 v[8:11], v[64:67], v[0:3], v[8:11]
	v_mfma_f32_16x16x32_bf16 v[8:11], v[70:73], v[0:3], v[8:11]
	s_waitcnt vmcnt(22)
	v_cvt_pk_bf16_f32 v64, v108, v109
	v_cvt_pk_bf16_f32 v65, v110, v111
	v_cvt_pk_bf16_f32 v66, v112, v113
	v_cvt_pk_bf16_f32 v67, v114, v115
	v_lshlrev_b32_e32 v190, 16, v64
	v_and_b32_e32 v191, 0xffff0000, v64
	v_sub_f32_e32 v190, v108, v190
	v_sub_f32_e32 v191, v109, v191
	v_cvt_pk_bf16_f32 v70, v190, v191
	v_lshlrev_b32_e32 v190, 16, v65
	v_and_b32_e32 v191, 0xffff0000, v65
	v_sub_f32_e32 v190, v110, v190
	v_sub_f32_e32 v191, v111, v191
	v_cvt_pk_bf16_f32 v71, v190, v191
	v_lshlrev_b32_e32 v190, 16, v66
	v_and_b32_e32 v191, 0xffff0000, v66
	v_sub_f32_e32 v190, v112, v190
	v_sub_f32_e32 v191, v113, v191
	v_cvt_pk_bf16_f32 v72, v190, v191
	v_lshlrev_b32_e32 v190, 16, v67
	v_and_b32_e32 v191, 0xffff0000, v67
	v_sub_f32_e32 v190, v114, v190
	v_sub_f32_e32 v191, v115, v191
	v_cvt_pk_bf16_f32 v73, v190, v191
	s_nop 1
	v_mfma_f32_16x16x32_bf16 v[4:7], v[64:67], v[20:23], 0
	v_mfma_f32_16x16x32_bf16 v[4:7], v[70:73], v[20:23], v[4:7]
	s_waitcnt vmcnt(20)
	v_cvt_pk_bf16_f32 v64, v116, v117
	v_cvt_pk_bf16_f32 v65, v118, v119
	v_cvt_pk_bf16_f32 v66, v120, v121
	v_cvt_pk_bf16_f32 v67, v122, v123
	v_lshlrev_b32_e32 v190, 16, v64
	v_and_b32_e32 v191, 0xffff0000, v64
	v_sub_f32_e32 v190, v116, v190
	v_sub_f32_e32 v191, v117, v191
	v_cvt_pk_bf16_f32 v70, v190, v191
	v_lshlrev_b32_e32 v190, 16, v65
	v_and_b32_e32 v191, 0xffff0000, v65
	v_sub_f32_e32 v190, v118, v190
	v_sub_f32_e32 v191, v119, v191
	v_cvt_pk_bf16_f32 v71, v190, v191
	v_lshlrev_b32_e32 v190, 16, v66
	v_and_b32_e32 v191, 0xffff0000, v66
	v_sub_f32_e32 v190, v120, v190
	v_sub_f32_e32 v191, v121, v191
	v_cvt_pk_bf16_f32 v72, v190, v191
	v_lshlrev_b32_e32 v190, 16, v67
	v_and_b32_e32 v191, 0xffff0000, v67
	v_sub_f32_e32 v190, v122, v190
	v_sub_f32_e32 v191, v123, v191
	v_cvt_pk_bf16_f32 v73, v190, v191
	s_nop 1
	v_mfma_f32_16x16x32_bf16 v[4:7], v[64:67], v[16:19], v[4:7]
	v_mfma_f32_16x16x32_bf16 v[4:7], v[70:73], v[16:19], v[4:7]
	s_waitcnt vmcnt(18)
	v_cvt_pk_bf16_f32 v64, v124, v125
	v_cvt_pk_bf16_f32 v65, v126, v127
	v_cvt_pk_bf16_f32 v66, v128, v129
	v_cvt_pk_bf16_f32 v67, v130, v131
	v_lshlrev_b32_e32 v190, 16, v64
	v_and_b32_e32 v191, 0xffff0000, v64
	v_sub_f32_e32 v190, v124, v190
	v_sub_f32_e32 v191, v125, v191
	v_cvt_pk_bf16_f32 v70, v190, v191
	v_lshlrev_b32_e32 v190, 16, v65
	v_and_b32_e32 v191, 0xffff0000, v65
	v_sub_f32_e32 v190, v126, v190
	v_sub_f32_e32 v191, v127, v191
	v_cvt_pk_bf16_f32 v71, v190, v191
	v_lshlrev_b32_e32 v190, 16, v66
	v_and_b32_e32 v191, 0xffff0000, v66
	v_sub_f32_e32 v190, v128, v190
	v_sub_f32_e32 v191, v129, v191
	v_cvt_pk_bf16_f32 v72, v190, v191
	v_lshlrev_b32_e32 v190, 16, v67
	v_and_b32_e32 v191, 0xffff0000, v67
	v_sub_f32_e32 v190, v130, v190
	v_sub_f32_e32 v191, v131, v191
	v_cvt_pk_bf16_f32 v73, v190, v191
	s_nop 1
	v_mfma_f32_16x16x32_bf16 v[4:7], v[64:67], v[12:15], v[4:7]
	v_mfma_f32_16x16x32_bf16 v[4:7], v[70:73], v[12:15], v[4:7]
	s_waitcnt vmcnt(16)
	v_cvt_pk_bf16_f32 v64, v132, v133
	v_cvt_pk_bf16_f32 v65, v134, v135
	v_cvt_pk_bf16_f32 v66, v136, v137
	v_cvt_pk_bf16_f32 v67, v138, v139
	v_lshlrev_b32_e32 v190, 16, v64
	v_and_b32_e32 v191, 0xffff0000, v64
	v_sub_f32_e32 v190, v132, v190
	v_sub_f32_e32 v191, v133, v191
	v_cvt_pk_bf16_f32 v70, v190, v191
	v_lshlrev_b32_e32 v190, 16, v65
	v_and_b32_e32 v191, 0xffff0000, v65
	v_sub_f32_e32 v190, v134, v190
	v_sub_f32_e32 v191, v135, v191
	v_cvt_pk_bf16_f32 v71, v190, v191
	v_lshlrev_b32_e32 v190, 16, v66
	v_and_b32_e32 v191, 0xffff0000, v66
	v_sub_f32_e32 v190, v136, v190
	v_sub_f32_e32 v191, v137, v191
	v_cvt_pk_bf16_f32 v72, v190, v191
	v_lshlrev_b32_e32 v190, 16, v67
	v_and_b32_e32 v191, 0xffff0000, v67
	v_sub_f32_e32 v190, v138, v190
	v_sub_f32_e32 v191, v139, v191
	v_cvt_pk_bf16_f32 v73, v190, v191
	s_nop 1
	v_mfma_f32_16x16x32_bf16 v[4:7], v[64:67], v[0:3], v[4:7]
	v_mfma_f32_16x16x32_bf16 v[4:7], v[70:73], v[0:3], v[4:7]
	s_waitcnt vmcnt(14)
	v_cvt_pk_bf16_f32 v64, v140, v141
	v_cvt_pk_bf16_f32 v65, v142, v143
	v_cvt_pk_bf16_f32 v66, v144, v145
	v_cvt_pk_bf16_f32 v67, v146, v147
	v_lshlrev_b32_e32 v190, 16, v64
	v_and_b32_e32 v191, 0xffff0000, v64
	v_sub_f32_e32 v190, v140, v190
	v_sub_f32_e32 v191, v141, v191
	v_cvt_pk_bf16_f32 v70, v190, v191
	v_lshlrev_b32_e32 v190, 16, v65
	v_and_b32_e32 v191, 0xffff0000, v65
	v_sub_f32_e32 v190, v142, v190
	v_sub_f32_e32 v191, v143, v191
	v_cvt_pk_bf16_f32 v71, v190, v191
	v_lshlrev_b32_e32 v190, 16, v66
	v_and_b32_e32 v191, 0xffff0000, v66
	v_sub_f32_e32 v190, v144, v190
	v_sub_f32_e32 v191, v145, v191
	v_cvt_pk_bf16_f32 v72, v190, v191
	v_lshlrev_b32_e32 v190, 16, v67
	v_and_b32_e32 v191, 0xffff0000, v67
	v_sub_f32_e32 v190, v146, v190
	v_sub_f32_e32 v191, v147, v191
	v_cvt_pk_bf16_f32 v73, v190, v191
	s_nop 1
	v_mfma_f32_16x16x32_bf16 v[28:31], v[64:67], v[20:23], 0
	v_mfma_f32_16x16x32_bf16 v[28:31], v[70:73], v[20:23], v[28:31]
	s_waitcnt vmcnt(12)
	v_cvt_pk_bf16_f32 v64, v148, v149
	v_cvt_pk_bf16_f32 v65, v150, v151
	v_cvt_pk_bf16_f32 v66, v152, v153
	v_cvt_pk_bf16_f32 v67, v154, v155
	v_lshlrev_b32_e32 v190, 16, v64
	v_and_b32_e32 v191, 0xffff0000, v64
	v_sub_f32_e32 v190, v148, v190
	v_sub_f32_e32 v191, v149, v191
	v_cvt_pk_bf16_f32 v70, v190, v191
	v_lshlrev_b32_e32 v190, 16, v65
	v_and_b32_e32 v191, 0xffff0000, v65
	v_sub_f32_e32 v190, v150, v190
	v_sub_f32_e32 v191, v151, v191
	v_cvt_pk_bf16_f32 v71, v190, v191
	v_lshlrev_b32_e32 v190, 16, v66
	v_and_b32_e32 v191, 0xffff0000, v66
	v_sub_f32_e32 v190, v152, v190
	v_sub_f32_e32 v191, v153, v191
	v_cvt_pk_bf16_f32 v72, v190, v191
	v_lshlrev_b32_e32 v190, 16, v67
	v_and_b32_e32 v191, 0xffff0000, v67
	v_sub_f32_e32 v190, v154, v190
	v_sub_f32_e32 v191, v155, v191
	v_cvt_pk_bf16_f32 v73, v190, v191
	s_nop 1
	v_mfma_f32_16x16x32_bf16 v[28:31], v[64:67], v[16:19], v[28:31]
	v_mfma_f32_16x16x32_bf16 v[28:31], v[70:73], v[16:19], v[28:31]
	s_waitcnt vmcnt(10)
	v_cvt_pk_bf16_f32 v64, v166, v167
	v_cvt_pk_bf16_f32 v65, v168, v169
	v_cvt_pk_bf16_f32 v66, v170, v171
	v_cvt_pk_bf16_f32 v67, v172, v173
	v_lshlrev_b32_e32 v190, 16, v64
	v_and_b32_e32 v191, 0xffff0000, v64
	v_sub_f32_e32 v190, v166, v190
	v_sub_f32_e32 v191, v167, v191
	v_cvt_pk_bf16_f32 v70, v190, v191
	v_lshlrev_b32_e32 v190, 16, v65
	v_and_b32_e32 v191, 0xffff0000, v65
	v_sub_f32_e32 v190, v168, v190
	v_sub_f32_e32 v191, v169, v191
	v_cvt_pk_bf16_f32 v71, v190, v191
	v_lshlrev_b32_e32 v190, 16, v66
	v_and_b32_e32 v191, 0xffff0000, v66
	v_sub_f32_e32 v190, v170, v190
	v_sub_f32_e32 v191, v171, v191
	v_cvt_pk_bf16_f32 v72, v190, v191
	v_lshlrev_b32_e32 v190, 16, v67
	v_and_b32_e32 v191, 0xffff0000, v67
	v_sub_f32_e32 v190, v172, v190
	v_sub_f32_e32 v191, v173, v191
	v_cvt_pk_bf16_f32 v73, v190, v191
	s_nop 1
	v_mfma_f32_16x16x32_bf16 v[28:31], v[64:67], v[12:15], v[28:31]
	v_mfma_f32_16x16x32_bf16 v[28:31], v[70:73], v[12:15], v[28:31]
	s_waitcnt vmcnt(8)
	v_cvt_pk_bf16_f32 v64, v174, v175
	v_cvt_pk_bf16_f32 v65, v176, v177
	v_cvt_pk_bf16_f32 v66, v178, v179
	v_cvt_pk_bf16_f32 v67, v180, v181
	v_lshlrev_b32_e32 v190, 16, v64
	v_and_b32_e32 v191, 0xffff0000, v64
	v_sub_f32_e32 v190, v174, v190
	v_sub_f32_e32 v191, v175, v191
	v_cvt_pk_bf16_f32 v70, v190, v191
	v_lshlrev_b32_e32 v190, 16, v65
	v_and_b32_e32 v191, 0xffff0000, v65
	v_sub_f32_e32 v190, v176, v190
	v_sub_f32_e32 v191, v177, v191
	v_cvt_pk_bf16_f32 v71, v190, v191
	v_lshlrev_b32_e32 v190, 16, v66
	v_and_b32_e32 v191, 0xffff0000, v66
	v_sub_f32_e32 v190, v178, v190
	v_sub_f32_e32 v191, v179, v191
	v_cvt_pk_bf16_f32 v72, v190, v191
	v_lshlrev_b32_e32 v190, 16, v67
	v_and_b32_e32 v191, 0xffff0000, v67
	v_sub_f32_e32 v190, v180, v190
	v_sub_f32_e32 v191, v181, v191
	v_cvt_pk_bf16_f32 v73, v190, v191
	s_nop 1
	v_mfma_f32_16x16x32_bf16 v[28:31], v[64:67], v[0:3], v[28:31]
	v_mfma_f32_16x16x32_bf16 v[28:31], v[70:73], v[0:3], v[28:31]
	s_waitcnt vmcnt(6)
	v_cvt_pk_bf16_f32 v64, v182, v183
	v_cvt_pk_bf16_f32 v65, v184, v185
	v_cvt_pk_bf16_f32 v66, v186, v187
	v_cvt_pk_bf16_f32 v67, v188, v189
	v_lshlrev_b32_e32 v190, 16, v64
	v_and_b32_e32 v191, 0xffff0000, v64
	v_sub_f32_e32 v190, v182, v190
	v_sub_f32_e32 v191, v183, v191
	v_cvt_pk_bf16_f32 v70, v190, v191
	v_lshlrev_b32_e32 v190, 16, v65
	v_and_b32_e32 v191, 0xffff0000, v65
	v_sub_f32_e32 v190, v184, v190
	v_sub_f32_e32 v191, v185, v191
	v_cvt_pk_bf16_f32 v71, v190, v191
	v_lshlrev_b32_e32 v190, 16, v66
	v_and_b32_e32 v191, 0xffff0000, v66
	v_sub_f32_e32 v190, v186, v190
	v_sub_f32_e32 v191, v187, v191
	v_cvt_pk_bf16_f32 v72, v190, v191
	v_lshlrev_b32_e32 v190, 16, v67
	v_and_b32_e32 v191, 0xffff0000, v67
	v_sub_f32_e32 v190, v188, v190
	v_sub_f32_e32 v191, v189, v191
	v_cvt_pk_bf16_f32 v73, v190, v191
	s_nop 1
	v_mfma_f32_16x16x32_bf16 v[24:27], v[64:67], v[20:23], 0
	v_mfma_f32_16x16x32_bf16 v[24:27], v[70:73], v[20:23], v[24:27]
	s_waitcnt vmcnt(4)
	v_cvt_pk_bf16_f32 v64, v214, v215
	v_cvt_pk_bf16_f32 v65, v216, v217
	v_cvt_pk_bf16_f32 v66, v218, v219
	v_cvt_pk_bf16_f32 v67, v220, v221
	v_lshlrev_b32_e32 v190, 16, v64
	v_and_b32_e32 v191, 0xffff0000, v64
	v_sub_f32_e32 v190, v214, v190
	v_sub_f32_e32 v191, v215, v191
	v_cvt_pk_bf16_f32 v70, v190, v191
	v_lshlrev_b32_e32 v190, 16, v65
	v_and_b32_e32 v191, 0xffff0000, v65
	v_sub_f32_e32 v190, v216, v190
	v_sub_f32_e32 v191, v217, v191
	v_cvt_pk_bf16_f32 v71, v190, v191
	v_lshlrev_b32_e32 v190, 16, v66
	v_and_b32_e32 v191, 0xffff0000, v66
	v_sub_f32_e32 v190, v218, v190
	v_sub_f32_e32 v191, v219, v191
	v_cvt_pk_bf16_f32 v72, v190, v191
	v_lshlrev_b32_e32 v190, 16, v67
	v_and_b32_e32 v191, 0xffff0000, v67
	v_sub_f32_e32 v190, v220, v190
	v_sub_f32_e32 v191, v221, v191
	v_cvt_pk_bf16_f32 v73, v190, v191
	s_nop 1
	v_mfma_f32_16x16x32_bf16 v[24:27], v[64:67], v[16:19], v[24:27]
	v_mfma_f32_16x16x32_bf16 v[24:27], v[70:73], v[16:19], v[24:27]
	s_waitcnt vmcnt(2)
	v_cvt_pk_bf16_f32 v64, v222, v223
	v_cvt_pk_bf16_f32 v65, v224, v225
	v_cvt_pk_bf16_f32 v66, v226, v227
	v_cvt_pk_bf16_f32 v67, v228, v229
	v_lshlrev_b32_e32 v190, 16, v64
	v_and_b32_e32 v191, 0xffff0000, v64
	v_sub_f32_e32 v190, v222, v190
	v_sub_f32_e32 v191, v223, v191
	v_cvt_pk_bf16_f32 v70, v190, v191
	v_lshlrev_b32_e32 v190, 16, v65
	v_and_b32_e32 v191, 0xffff0000, v65
	v_sub_f32_e32 v190, v224, v190
	v_sub_f32_e32 v191, v225, v191
	v_cvt_pk_bf16_f32 v71, v190, v191
	v_lshlrev_b32_e32 v190, 16, v66
	v_and_b32_e32 v191, 0xffff0000, v66
	v_sub_f32_e32 v190, v226, v190
	v_sub_f32_e32 v191, v227, v191
	v_cvt_pk_bf16_f32 v72, v190, v191
	v_lshlrev_b32_e32 v190, 16, v67
	v_and_b32_e32 v191, 0xffff0000, v67
	v_sub_f32_e32 v190, v228, v190
	v_sub_f32_e32 v191, v229, v191
	v_cvt_pk_bf16_f32 v73, v190, v191
	s_nop 1
	v_mfma_f32_16x16x32_bf16 v[24:27], v[64:67], v[12:15], v[24:27]
	v_mfma_f32_16x16x32_bf16 v[24:27], v[70:73], v[12:15], v[24:27]
	s_waitcnt vmcnt(0)
	v_cvt_pk_bf16_f32 v64, v230, v231
	v_cvt_pk_bf16_f32 v65, v232, v233
	v_cvt_pk_bf16_f32 v66, v234, v235
	v_cvt_pk_bf16_f32 v67, v236, v237
	v_lshlrev_b32_e32 v190, 16, v64
	v_and_b32_e32 v191, 0xffff0000, v64
	v_sub_f32_e32 v190, v230, v190
	v_sub_f32_e32 v191, v231, v191
	v_cvt_pk_bf16_f32 v70, v190, v191
	v_lshlrev_b32_e32 v190, 16, v65
	v_and_b32_e32 v191, 0xffff0000, v65
	v_sub_f32_e32 v190, v232, v190
	v_sub_f32_e32 v191, v233, v191
	v_cvt_pk_bf16_f32 v71, v190, v191
	v_lshlrev_b32_e32 v190, 16, v66
	v_and_b32_e32 v191, 0xffff0000, v66
	v_sub_f32_e32 v190, v234, v190
	v_sub_f32_e32 v191, v235, v191
	v_cvt_pk_bf16_f32 v72, v190, v191
	v_lshlrev_b32_e32 v190, 16, v67
	v_and_b32_e32 v191, 0xffff0000, v67
	v_sub_f32_e32 v190, v236, v190
	v_sub_f32_e32 v191, v237, v191
	v_cvt_pk_bf16_f32 v73, v190, v191
	s_nop 1
	v_mfma_f32_16x16x32_bf16 v[24:27], v[64:67], v[0:3], v[24:27]
	v_mfma_f32_16x16x32_bf16 v[24:27], v[70:73], v[0:3], v[24:27]
	s_nop 7
	s_nop 1
	s_branch .LBB0_281
.LBB0_275:
	v_mov_b32_e32 v5, 0
	v_mov_b32_e32 v6, 0
	v_mov_b32_e32 v7, 0
	v_mov_b32_e32 v24, 0
	v_mov_b32_e32 v25, 0
	v_mov_b32_e32 v26, 0
	v_mov_b32_e32 v27, 0
	v_mov_b32_e32 v28, 0
	v_mov_b32_e32 v29, 0
	v_mov_b32_e32 v30, 0
	v_mov_b32_e32 v31, 0
